# scan: one static s_setprio 1 for the wave half that issues the operand DMA (late MFMA starters), reset after the chunk barrier
# speedup vs baseline: 1.0014x; 1.0014x over previous
.LBB0_1090:
	v_mov_b32_e32 v40, v125
	s_add_i32 s64, s19, 1
	s_cmp_ge_u32 s64, s22
	v_and_b32_e32 v135, 15, v40
	v_ashrrev_i32_e32 v136, 4, v40
	s_cbranch_scc1 .LBB0_1092
	s_add_i32 s20, s63, s19
	s_ashr_i32 s21, s20, 31
	s_lshl_b64 s[58:59], s[20:21], 2
	s_add_u32 s58, s24, s58
	s_addc_u32 s59, s25, s59
	s_mul_hi_i32 s21, s20, 0x16000
	s_mul_i32 s20, s20, 0x16000
	v_lshlrev_b32_e32 v41, 4, v40
	s_add_u32 s20, s31, s20
	v_add_u32_e32 v42, s35, v41
	s_addc_u32 s21, s34, s21
	v_lshrrev_b32_e32 v43, 8, v42
	global_load_dword v134, v173, s[58:59]
	s_add_u32 s58, s20, 0x8000
	v_xor_b32_e32 v43, v43, v40
	s_addc_u32 s59, s21, 0
	v_lshlrev_b32_e32 v43, 4, v43
	v_and_b32_e32 v42, 0xffffff00, v42
	s_bitcmp1_b32 s64, 0
	v_and_or_b32 v172, v43, s69, v42
	s_cselect_b32 s65, 0xe000, 0
	v_lshl_add_u64 v[42:43], s[58:59], 0, v[172:173]
	s_add_i32 s65, s36, s65
	s_cmp_lt_u32 s28, 64
	s_cbranch_scc1 .Lscan_nodma
	s_mov_b32 m0, s65
	s_nop 0
	global_load_lds_dwordx4 v[42:43], off
	global_load_lds_dwordx4 v[42:43], off offset:-4096
	v_add_u32_e32 v42, s37, v41
	v_lshrrev_b32_e32 v43, 8, v42
	v_xor_b32_e32 v43, v43, v40
	v_lshlrev_b32_e32 v43, 4, v43
	v_and_b32_e32 v42, 0xffffff00, v42
	v_and_or_b32 v172, v43, s69, v42
	v_lshl_add_u64 v[42:43], s[58:59], 0, v[172:173]
	s_add_i32 s66, s65, 0x2000
	s_mov_b32 m0, s66
	s_nop 0
	global_load_lds_dwordx4 v[42:43], off
	global_load_lds_dwordx4 v[42:43], off offset:-4096
	v_add_u32_e32 v42, s39, v41
	v_lshrrev_b32_e32 v43, 8, v42
	v_xor_b32_e32 v43, v43, v40
	v_lshlrev_b32_e32 v43, 4, v43
	v_and_b32_e32 v42, 0xffffff00, v42
	v_and_or_b32 v172, v43, s69, v42
	v_lshl_add_u64 v[42:43], s[58:59], 0, v[172:173]
	s_add_i32 s66, s65, 0x4000
	s_mov_b32 m0, s66
	s_nop 0
	global_load_lds_dwordx4 v[42:43], off
	global_load_lds_dwordx4 v[42:43], off offset:-4096
	v_add_u32_e32 v42, s41, v41
	v_lshrrev_b32_e32 v43, 8, v42
	v_xor_b32_e32 v43, v43, v40
	v_lshlrev_b32_e32 v43, 4, v43
	v_and_b32_e32 v42, 0xffffff00, v42
	v_and_or_b32 v172, v43, s69, v42
	v_lshl_add_u64 v[42:43], s[58:59], 0, v[172:173]
	s_add_i32 s66, s65, 0x6000
	s_mov_b32 m0, s66
	s_nop 0
	global_load_lds_dwordx4 v[42:43], off
	global_load_lds_dwordx4 v[42:43], off offset:-4096
	v_add_u32_e32 v42, s45, v41
	v_lshrrev_b32_e32 v43, 8, v42
	v_xor_b32_e32 v43, v43, v40
	v_lshlrev_b32_e32 v43, 4, v43
	v_and_b32_e32 v42, 0xffffff80, v42
	v_and_or_b32 v172, v43, s93, v42
	v_lshl_add_u64 v[42:43], s[58:59], 0, v[172:173]
	s_add_i32 s66, s65, 0x8000
	s_mov_b32 m0, s66
	s_nop 0
	global_load_lds_dwordx4 v[42:43], off
	global_load_lds_dwordx4 v[42:43], off offset:-4096
	v_add_u32_e32 v42, s47, v41
	v_lshrrev_b32_e32 v43, 8, v42
	v_xor_b32_e32 v43, v43, v40
	v_lshlrev_b32_e32 v43, 4, v43
	v_and_b32_e32 v42, 0xffffff80, v42
	v_and_or_b32 v172, v43, s93, v42
	v_lshl_add_u64 v[42:43], s[58:59], 0, v[172:173]
	v_add_u32_e32 v41, s49, v41
	s_add_i32 s66, s65, 0xa000
	s_mov_b32 m0, s66
	s_nop 0
	global_load_lds_dwordx4 v[42:43], off
	global_load_lds_dwordx4 v[42:43], off offset:-4096
	v_lshrrev_b32_e32 v42, 8, v41
	v_xor_b32_e32 v42, v42, v40
	v_lshlrev_b32_e32 v42, 4, v42
	v_and_b32_e32 v41, 0xffffff80, v41
	v_and_or_b32 v172, v42, s93, v41
	v_lshl_add_u64 v[42:43], s[58:59], 0, v[172:173]
	s_add_i32 s65, s65, 0xc000
	s_mov_b32 m0, s65
	s_nop 0
	global_load_lds_dwordx4 v[42:43], off
	global_load_lds_dwordx4 v[42:43], off offset:-4096
	s_setprio 1

.LBB0_1092:
	v_lshlrev_b32_e32 v146, 16, v32
	v_and_b32_e32 v147, 0xffff0000, v32
	v_lshlrev_b32_e32 v148, 16, v33
	v_and_b32_e32 v149, 0xffff0000, v33
	v_xor_b32_e32 v32, 0x80000000, v1
	v_xor_b32_e32 v33, 0x80000000, v0
	v_cvt_pk_bf16_f32 v150, v33, v32
	v_xor_b32_e32 v32, 0x80000000, v2
	v_xor_b32_e32 v33, 0x80000000, v3
	v_cvt_pk_bf16_f32 v151, v32, v33
	v_xor_b32_e32 v32, 0x80000000, v4
	v_xor_b32_e32 v33, 0x80000000, v5
	v_cvt_pk_bf16_f32 v152, v32, v33
	v_xor_b32_e32 v32, 0x80000000, v6
	v_xor_b32_e32 v33, 0x80000000, v7
	v_cvt_pk_bf16_f32 v153, v32, v33
	v_xor_b32_e32 v32, 0x80000000, v8
	v_xor_b32_e32 v33, 0x80000000, v9
	v_cvt_pk_bf16_f32 v154, v32, v33
	v_xor_b32_e32 v32, 0x80000000, v10
	v_xor_b32_e32 v33, 0x80000000, v11
	v_cvt_pk_bf16_f32 v155, v32, v33
	v_xor_b32_e32 v32, 0x80000000, v12
	v_xor_b32_e32 v33, 0x80000000, v13
	v_cvt_pk_bf16_f32 v156, v32, v33
	v_xor_b32_e32 v32, 0x80000000, v14
	v_xor_b32_e32 v33, 0x80000000, v15
	v_cvt_pk_bf16_f32 v157, v32, v33
	v_xor_b32_e32 v32, 0x80000000, v16
	v_xor_b32_e32 v33, 0x80000000, v17
	v_cvt_pk_bf16_f32 v158, v32, v33
	v_xor_b32_e32 v32, 0x80000000, v18
	v_xor_b32_e32 v33, 0x80000000, v19
	v_cvt_pk_bf16_f32 v159, v32, v33
	v_xor_b32_e32 v32, 0x80000000, v20
	v_xor_b32_e32 v33, 0x80000000, v21
	v_cvt_pk_bf16_f32 v160, v32, v33
	v_xor_b32_e32 v32, 0x80000000, v22
	v_xor_b32_e32 v33, 0x80000000, v23
	v_cvt_pk_bf16_f32 v161, v32, v33
	v_xor_b32_e32 v32, 0x80000000, v28
	v_xor_b32_e32 v33, 0x80000000, v29
	s_bitcmp1_b32 s19, 0
	v_cvt_pk_bf16_f32 v162, v32, v33
	v_xor_b32_e32 v32, 0x80000000, v30
	v_xor_b32_e32 v33, 0x80000000, v31
	s_cselect_b32 s19, 0xe000, 0
	v_cvt_pk_bf16_f32 v163, v32, v33
	v_xor_b32_e32 v32, 0x80000000, v24
	v_xor_b32_e32 v33, 0x80000000, v25
	s_add_i32 s19, s19, 0
	v_cvt_pk_bf16_f32 v164, v32, v33
	v_xor_b32_e32 v32, 0x80000000, v26
	v_xor_b32_e32 v33, 0x80000000, v27
	v_and_b32_e32 v43, -16, v40
	v_cvt_pk_bf16_f32 v165, v32, v33
	v_lshlrev_b32_e32 v32, 4, v135
	v_lshl_add_u32 v33, v135, 8, s19
	v_add_u32_e32 v170, 64, v43
	v_add_u32_e32 v172, 0x80, v43
	v_add_u32_e32 v186, 0xc0, v43
	v_xad_u32 v137, v32, v43, v33
	v_xad_u32 v171, v170, v32, v33
	v_xad_u32 v172, v172, v32, v33
	v_xad_u32 v210, v186, v32, v33
	v_lshlrev_b32_e32 v138, 16, v38
	v_and_b32_e32 v139, 0xffff0000, v38
	v_lshlrev_b32_e32 v140, 16, v39
	v_and_b32_e32 v141, 0xffff0000, v39
	v_lshlrev_b32_e32 v42, 3, v40
	ds_read_b128 v[38:41], v137
	ds_read_b128 v[166:169], v171
	ds_read_b128 v[182:185], v172
	ds_read_b128 v[186:189], v210
	ds_read_b128 v[190:193], v137 offset:4096
	ds_read_b128 v[194:197], v171 offset:4096
	ds_read_b128 v[198:201], v172 offset:4096
	ds_read_b128 v[202:205], v210 offset:4096
	v_lshlrev_b32_e32 v142, 16, v34
	v_and_b32_e32 v143, 0xffff0000, v34
	v_lshlrev_b32_e32 v144, 16, v35
	v_and_b32_e32 v145, 0xffff0000, v35
	v_lshlrev_b32_e32 v34, 16, v36
	v_and_b32_e32 v35, 0xffff0000, v36
	v_lshlrev_b32_e32 v36, 16, v37
	v_and_b32_e32 v37, 0xffff0000, v37
	s_waitcnt lgkmcnt(7)
	v_mfma_f32_16x16x32_bf16 v[38:41], v[38:41], v[150:153], v[138:141]
	s_waitcnt lgkmcnt(6)
	v_mfma_f32_16x16x32_bf16 v[38:41], v[166:169], v[154:157], v[38:41]
	s_waitcnt lgkmcnt(5)
	v_mfma_f32_16x16x32_bf16 v[38:41], v[182:185], v[158:161], v[38:41]
	s_waitcnt lgkmcnt(4)
	v_mfma_f32_16x16x32_bf16 v[38:41], v[186:189], v[162:165], v[38:41]
	ds_read_b128 v[138:141], v137 offset:8192
	ds_read_b128 v[166:169], v171 offset:8192
	ds_read_b128 v[182:185], v172 offset:8192
	ds_read_b128 v[186:189], v210 offset:8192
	s_waitcnt lgkmcnt(7)
	v_mfma_f32_16x16x32_bf16 v[142:145], v[190:193], v[150:153], v[142:145]
	s_waitcnt lgkmcnt(6)
	v_mfma_f32_16x16x32_bf16 v[142:145], v[194:197], v[154:157], v[142:145]
	s_waitcnt lgkmcnt(5)
	v_mfma_f32_16x16x32_bf16 v[142:145], v[198:201], v[158:161], v[142:145]
	s_waitcnt lgkmcnt(4)
	v_mfma_f32_16x16x32_bf16 v[142:145], v[202:205], v[162:165], v[142:145]
	ds_read_b128 v[190:193], v137 offset:12288
	ds_read_b128 v[194:197], v171 offset:12288
	ds_read_b128 v[198:201], v172 offset:12288
	ds_read_b128 v[202:205], v210 offset:12288
	s_waitcnt lgkmcnt(7)
	v_mfma_f32_16x16x32_bf16 v[32:35], v[138:141], v[150:153], v[34:37]
	s_waitcnt lgkmcnt(6)
	v_mfma_f32_16x16x32_bf16 v[32:35], v[166:169], v[154:157], v[32:35]
	s_waitcnt lgkmcnt(5)
	v_mfma_f32_16x16x32_bf16 v[32:35], v[182:185], v[158:161], v[32:35]
	s_waitcnt lgkmcnt(4)
	v_mfma_f32_16x16x32_bf16 v[32:35], v[186:189], v[162:165], v[32:35]
	ds_read_b128 v[138:141], v137 offset:16384
	ds_read_b128 v[166:169], v171 offset:16384
	ds_read_b128 v[182:185], v172 offset:16384
	ds_read_b128 v[186:189], v210 offset:16384
	s_waitcnt lgkmcnt(7)
	v_mfma_f32_16x16x32_bf16 v[146:149], v[190:193], v[150:153], v[146:149]
	s_waitcnt lgkmcnt(6)
	v_mfma_f32_16x16x32_bf16 v[146:149], v[194:197], v[154:157], v[146:149]
	s_waitcnt lgkmcnt(5)
	v_mfma_f32_16x16x32_bf16 v[146:149], v[198:201], v[158:161], v[146:149]
	s_waitcnt lgkmcnt(4)
	v_mfma_f32_16x16x32_bf16 v[146:149], v[202:205], v[162:165], v[146:149]
	ds_read_b128 v[190:193], v137 offset:20480
	ds_read_b128 v[194:197], v171 offset:20480
	ds_read_b128 v[198:201], v172 offset:20480
	ds_read_b128 v[202:205], v210 offset:20480
	v_xor_b32_e32 v153, 0x80008000, v153
	v_xor_b32_e32 v152, 0x80008000, v152
	v_xor_b32_e32 v151, 0x80008000, v151
	v_xor_b32_e32 v150, 0x80008000, v150
	v_xor_b32_e32 v157, 0x80008000, v157
	v_xor_b32_e32 v156, 0x80008000, v156
	s_waitcnt lgkmcnt(7)
	v_mfma_f32_16x16x32_bf16 v[138:141], v[138:141], v[150:153], 0
	v_xor_b32_e32 v155, 0x80008000, v155
	v_xor_b32_e32 v154, 0x80008000, v154
	v_xor_b32_e32 v161, 0x80008000, v161
	v_xor_b32_e32 v160, 0x80008000, v160
	s_waitcnt lgkmcnt(6)
	v_mfma_f32_16x16x32_bf16 v[138:141], v[166:169], v[154:157], v[138:141]
	v_xor_b32_e32 v159, 0x80008000, v159
	v_xor_b32_e32 v158, 0x80008000, v158
	v_xor_b32_e32 v165, 0x80008000, v165
	v_xor_b32_e32 v164, 0x80008000, v164
	s_waitcnt lgkmcnt(5)
	v_mfma_f32_16x16x32_bf16 v[138:141], v[182:185], v[158:161], v[138:141]
	v_xor_b32_e32 v163, 0x80008000, v163
	v_xor_b32_e32 v162, 0x80008000, v162
	s_waitcnt lgkmcnt(4)
	s_nop 0
	v_mfma_f32_16x16x32_bf16 v[138:141], v[186:189], v[162:165], v[138:141]
	ds_read_b128 v[166:169], v137 offset:24576
	ds_read_b128 v[182:185], v171 offset:24576
	ds_read_b128 v[186:189], v172 offset:24576
	ds_read_b128 v[206:209], v210 offset:24576
	s_waitcnt lgkmcnt(7)
	v_mfma_f32_16x16x32_bf16 v[190:193], v[190:193], v[150:153], 0
	s_waitcnt lgkmcnt(6)
	v_mfma_f32_16x16x32_bf16 v[190:193], v[194:197], v[154:157], v[190:193]
	s_waitcnt lgkmcnt(5)
	v_mfma_f32_16x16x32_bf16 v[190:193], v[198:201], v[158:161], v[190:193]
	s_waitcnt lgkmcnt(4)
	v_mfma_f32_16x16x32_bf16 v[190:193], v[202:205], v[162:165], v[190:193]
	ds_read_b128 v[194:197], v137 offset:28672
	ds_read_b128 v[198:201], v171 offset:28672
	ds_read_b128 v[202:205], v172 offset:28672
	ds_read_b128 v[210:213], v210 offset:28672
	s_waitcnt lgkmcnt(7)
	v_mfma_f32_16x16x32_bf16 v[166:169], v[166:169], v[150:153], 0
	v_and_b32_e32 v36, 0x70, v42
	v_lshl_add_u32 v37, v135, 7, s19
	v_xad_u32 v137, v36, v43, v37
	s_waitcnt lgkmcnt(6)
	v_mfma_f32_16x16x32_bf16 v[166:169], v[182:185], v[154:157], v[166:169]
	v_xad_u32 v170, v170, v36, v37
	ds_read_b128 v[182:185], v137 offset:49152
	s_waitcnt lgkmcnt(6)
	v_mfma_f32_16x16x32_bf16 v[166:169], v[186:189], v[158:161], v[166:169]
	s_waitcnt lgkmcnt(5)
	v_mfma_f32_16x16x32_bf16 v[166:169], v[206:209], v[162:165], v[166:169]
	ds_read_b128 v[186:189], v170 offset:49152
	ds_read_b128 v[206:209], v137 offset:51200
	ds_read_b128 v[230:233], v170 offset:51200
	s_waitcnt lgkmcnt(7)
	v_mfma_f32_16x16x32_bf16 v[150:153], v[194:197], v[150:153], 0
	s_waitcnt lgkmcnt(6)
	v_mfma_f32_16x16x32_bf16 v[150:153], v[198:201], v[154:157], v[150:153]
	s_waitcnt lgkmcnt(5)
	v_mfma_f32_16x16x32_bf16 v[150:153], v[202:205], v[158:161], v[150:153]
	ds_read_b128 v[154:157], v137 offset:53248
	ds_read_b128 v[158:161], v137 offset:55296
	ds_read_b128 v[194:197], v170 offset:53248
	ds_read_b128 v[198:201], v170 offset:55296
	s_waitcnt lgkmcnt(8)
	v_mfma_f32_16x16x32_bf16 v[150:153], v[210:213], v[162:165], v[150:153]
	v_cvt_pk_bf16_f32 v162, v38, v39
	v_cvt_pk_bf16_f32 v163, v40, v41
	v_cvt_pk_bf16_f32 v164, v142, v143
	v_cvt_pk_bf16_f32 v165, v144, v145
	v_cvt_pk_bf16_f32 v142, v32, v33
	v_cvt_pk_bf16_f32 v143, v34, v35
	s_waitcnt lgkmcnt(7)
	v_mfma_f32_16x16x32_bf16 v[36:39], v[182:185], v[162:165], v[138:141]
	v_cvt_pk_bf16_f32 v144, v146, v147
	v_cvt_pk_bf16_f32 v145, v148, v149
	s_waitcnt lgkmcnt(5)
	v_mfma_f32_16x16x32_bf16 v[32:35], v[206:209], v[162:165], v[190:193]
	v_mfma_f32_16x16x32_bf16 v[138:141], v[186:189], v[142:145], v[36:39]
	ds_read_b128 v[146:149], v137 offset:32768
	ds_read_b128 v[182:185], v137 offset:34816
	ds_read_b128 v[186:189], v170 offset:32768
	ds_read_b128 v[190:193], v170 offset:34816
	s_waitcnt lgkmcnt(8)
	v_mfma_f32_16x16x32_bf16 v[40:43], v[230:233], v[142:145], v[32:35]
	s_waitcnt lgkmcnt(7)
	v_mfma_f32_16x16x32_bf16 v[32:35], v[154:157], v[162:165], v[166:169]
	s_waitcnt lgkmcnt(5)
	v_mfma_f32_16x16x32_bf16 v[36:39], v[194:197], v[142:145], v[32:35]
	v_mfma_f32_16x16x32_bf16 v[32:35], v[158:161], v[162:165], v[150:153]
	s_nop 2
	ds_read_b128 v[150:153], v137 offset:36864
	ds_read_b128 v[154:157], v170 offset:36864
	ds_read_b128 v[158:161], v137 offset:38912
	ds_read_b128 v[166:169], v170 offset:38912
	s_waitcnt lgkmcnt(8)
	v_mfma_f32_16x16x32_bf16 v[32:35], v[198:201], v[142:145], v[32:35]
	v_mul_f32_e64 v2, v124, v2
	v_mul_f32_e64 v3, v124, v3
	v_pk_mul_f32 v[0:1], v[124:125], v[0:1] op_sel_hi:[0,1]
	v_pk_mul_f32 v[6:7], v[124:125], v[6:7] op_sel_hi:[0,1]
	v_pk_mul_f32 v[4:5], v[124:125], v[4:5] op_sel_hi:[0,1]
	s_waitcnt lgkmcnt(7)
	v_mfma_f32_16x16x32_bf16 v[0:3], v[146:149], v[162:165], v[0:3]
	s_waitcnt lgkmcnt(6)
	v_mfma_f32_16x16x32_bf16 v[4:7], v[182:185], v[162:165], v[4:7]
	s_waitcnt lgkmcnt(5)
	v_mfma_f32_16x16x32_bf16 v[0:3], v[186:189], v[142:145], v[0:3]
	s_waitcnt lgkmcnt(4)
	v_mfma_f32_16x16x32_bf16 v[4:7], v[190:193], v[142:145], v[4:7]
	ds_read_b128 v[146:149], v137 offset:40960
	ds_read_b128 v[182:185], v170 offset:40960
	ds_read_b128 v[186:189], v137 offset:43008
	ds_read_b128 v[190:193], v170 offset:43008
	v_pk_mul_f32 v[10:11], v[124:125], v[10:11] op_sel_hi:[0,1]
	v_pk_mul_f32 v[8:9], v[124:125], v[8:9] op_sel_hi:[0,1]
	v_pk_mul_f32 v[14:15], v[124:125], v[14:15] op_sel_hi:[0,1]
	v_pk_mul_f32 v[12:13], v[124:125], v[12:13] op_sel_hi:[0,1]
	s_waitcnt lgkmcnt(7)
	v_mfma_f32_16x16x32_bf16 v[8:11], v[150:153], v[162:165], v[8:11]
	s_waitcnt lgkmcnt(5)
	v_mfma_f32_16x16x32_bf16 v[12:15], v[158:161], v[162:165], v[12:15]
	v_mfma_f32_16x16x32_bf16 v[8:11], v[154:157], v[142:145], v[8:11]
	s_waitcnt lgkmcnt(4)
	v_mfma_f32_16x16x32_bf16 v[12:15], v[166:169], v[142:145], v[12:15]
	ds_read_b128 v[150:153], v137 offset:45056
	ds_read_b128 v[154:157], v170 offset:45056
	ds_read_b128 v[158:161], v137 offset:47104
	ds_read_b128 v[166:169], v170 offset:47104
	v_pk_mul_f32 v[18:19], v[124:125], v[18:19] op_sel_hi:[0,1]
	v_pk_mul_f32 v[16:17], v[124:125], v[16:17] op_sel_hi:[0,1]
	v_pk_mul_f32 v[22:23], v[124:125], v[22:23] op_sel_hi:[0,1]
	v_pk_mul_f32 v[20:21], v[124:125], v[20:21] op_sel_hi:[0,1]
	s_waitcnt lgkmcnt(7)
	v_mfma_f32_16x16x32_bf16 v[16:19], v[146:149], v[162:165], v[16:19]
	s_waitcnt lgkmcnt(5)
	v_mfma_f32_16x16x32_bf16 v[20:23], v[186:189], v[162:165], v[20:23]
	v_mfma_f32_16x16x32_bf16 v[16:19], v[182:185], v[142:145], v[16:19]
	s_waitcnt lgkmcnt(4)
	v_mfma_f32_16x16x32_bf16 v[20:23], v[190:193], v[142:145], v[20:23]
	s_ashr_i32 s19, s18, 31
	s_lshl_b64 s[20:21], s[18:19], 11
	v_pk_mul_f32 v[30:31], v[124:125], v[30:31] op_sel_hi:[0,1]
	v_pk_mul_f32 v[28:29], v[124:125], v[28:29] op_sel_hi:[0,1]
	v_pk_mul_f32 v[26:27], v[124:125], v[26:27] op_sel_hi:[0,1]
	v_pk_mul_f32 v[24:25], v[124:125], v[24:25] op_sel_hi:[0,1]
	s_add_u32 s20, s23, s20
	s_addc_u32 s21, s62, s21
	s_waitcnt lgkmcnt(3)
	v_mfma_f32_16x16x32_bf16 v[28:31], v[150:153], v[162:165], v[28:31]
	s_andn2_b64 vcc, exec, s[12:13]
	s_waitcnt lgkmcnt(1)
	v_mfma_f32_16x16x32_bf16 v[24:27], v[158:161], v[162:165], v[24:27]
	v_mfma_f32_16x16x32_bf16 v[28:31], v[154:157], v[142:145], v[28:31]
	s_waitcnt lgkmcnt(0)
	v_mfma_f32_16x16x32_bf16 v[24:27], v[166:169], v[142:145], v[24:27]
	s_cbranch_vccnz .Lscan_smp
	s_bitcmp1_b32 s64, 0
	s_mov_b32 s65, 0x20010
	s_cselect_b32 s65, 0x1c000, s65
	v_lshlrev_b32_e32 v137, 10, v136
	s_lshl_b32 s66, s28, 1
	v_lshl_add_u32 v137, v135, 1, v137
	v_lshlrev_b32_e32 v124, 5, v136
	v_lshlrev_b32_e32 v171, 11, v136
	v_xor_b32_e32 v124, s66, v124
	v_add3_u32 v137, v137, v124, s65
	v_lshl_add_u32 v171, v135, 4, v171
	v_cvt_pk_bf16_f32 v124, v138, v138
	ds_write_b16 v137, v124
	v_cvt_pk_bf16_f32 v124, v139, v139
	ds_write_b16 v137, v124 offset:256
	v_cvt_pk_bf16_f32 v124, v140, v140
	ds_write_b16 v137, v124 offset:512
	v_cvt_pk_bf16_f32 v124, v141, v141
	ds_write_b16 v137, v124 offset:768
	v_cvt_pk_bf16_f32 v124, v40, v40
	ds_write_b16 v137, v124 offset:4096
	v_cvt_pk_bf16_f32 v124, v41, v41
	ds_write_b16 v137, v124 offset:4352
	v_cvt_pk_bf16_f32 v124, v42, v42
	ds_write_b16 v137, v124 offset:4608
	v_cvt_pk_bf16_f32 v124, v43, v43
	ds_write_b16 v137, v124 offset:4864
	v_cvt_pk_bf16_f32 v124, v36, v36
	ds_write_b16 v137, v124 offset:8192
	v_cvt_pk_bf16_f32 v124, v37, v37
	ds_write_b16 v137, v124 offset:8448
	v_cvt_pk_bf16_f32 v124, v38, v38
	ds_write_b16 v137, v124 offset:8704
	v_cvt_pk_bf16_f32 v124, v39, v39
	ds_write_b16 v137, v124 offset:8960
	v_cvt_pk_bf16_f32 v124, v32, v32
	ds_write_b16 v137, v124 offset:12288
	v_cvt_pk_bf16_f32 v124, v33, v33
	ds_write_b16 v137, v124 offset:12544
	v_cvt_pk_bf16_f32 v124, v34, v34
	ds_write_b16 v137, v124 offset:12800
	v_cvt_pk_bf16_f32 v124, v35, v35
	ds_write_b16 v137, v124 offset:13056
	s_lshl_b32 s66, s28, 1
	s_and_b32 s66, s66, 0x60
	v_lshlrev_b32_e32 v170, 4, v125
	v_xor_b32_e32 v170, s66, v170
	s_lshl_b32 s66, s28, 6
	s_add_i32 s66, s66, s65
	v_add_u32_e32 v170, s66, v170
	s_lshl_b32 s66, s28, 9
	v_add_u32_e32 v171, s66, v171
	s_add_u32 s58, s20, 0x10000
	s_addc_u32 s59, s21, 0
	s_add_i32 s18, s18, 64
	s_waitcnt vmcnt(0) lgkmcnt(0)
	s_barrier
	s_setprio 0
	ds_read_b128 v[146:149], v170
	ds_read_b128 v[150:153], v170 offset:8192
	v_permlane16_swap_b32_e32 v126, v128
	v_permlane16_swap_b32_e32 v127, v129
	v_permlane16_swap_b32_e32 v130, v132
	v_permlane16_swap_b32_e32 v131, v133
	s_nop 1
	v_permlane32_swap_b32_e32 v126, v128
	v_permlane32_swap_b32_e32 v127, v129
	v_permlane32_swap_b32_e32 v130, v132
	v_permlane32_swap_b32_e32 v131, v133
	s_nop 1
	v_mov_b64_e32 v[38:39], v[126:127]
	v_mov_b64_e32 v[34:35], v[128:129]
	v_mov_b64_e32 v[36:37], v[130:131]
	v_mov_b64_e32 v[32:33], v[132:133]
	v_mov_b32_e32 v124, v134
	s_cmp_eq_u32 s22, s64
	s_mov_b32 s19, s64
	s_waitcnt lgkmcnt(1)
	global_store_dwordx4 v171, v[146:149], s[20:21]
	s_waitcnt lgkmcnt(0)
	global_store_dwordx4 v171, v[150:153], s[58:59]
	s_cbranch_scc1 .LBB0_1083
	s_branch .LBB0_1090
